# v74 plus in-projection phase: the 94 workgroups that own 8 tiles start about 12us late (3 x s_sleep 127) so their tile-store bursts fall inside the other workgroups' main loops
# baseline (speedup 1.0000x reference)
.LBB0_376:
	s_lshr_b32 s0, s91, 3
	s_and_b32 s0, s0, 3
	s_mul_i32 s0, s0, 0
	s_cmp_lt_u32 s91, 162
	s_cselect_b32 s0, s0, 3
	s_cmp_eq_u32 s0, 0
	s_cbranch_scc1 .Lstag_done_i
.Lstag_loop_i:
	s_sleep 127
	s_add_i32 s0, s0, -1
	s_cmp_lg_u32 s0, 0
	s_cbranch_scc1 .Lstag_loop_i
